# S5 scan pass 1: loop body hand-written (scalar v_fma_f32 recurrence, 4 per step, instead of packed-f32 sequence) on top of prologue load batching
# speedup vs baseline: 1.0091x; 1.0091x over previous
.LBB0_848:
	v_add_u32_e32 v252, v139, v141
	v_add_u32_e32 v253, s86, v140
	v_cndmask_b32_e64 v184, v80, 0, s[10:11]
	v_cndmask_b32_e64 v185, v81, 0, s[10:11]
	v_cndmask_b32_e64 v186, v82, 0, s[10:11]
	v_cndmask_b32_e64 v187, v83, 0, s[10:11]
	s_nop 1
	v_mfma_f32_16x16x32_bf16 v[188:191], v[184:187], v[0:3], 0
	v_mfma_f32_16x16x32_bf16 v[192:195], v[184:187], v[4:7], 0
	v_mfma_f32_16x16x32_bf16 v[196:199], v[184:187], v[8:11], 0
	v_mfma_f32_16x16x32_bf16 v[200:203], v[184:187], v[12:15], 0
	v_mfma_f32_16x16x32_bf16 v[204:207], v[184:187], v[16:19], 0
	v_mfma_f32_16x16x32_bf16 v[208:211], v[184:187], v[20:23], 0
	v_mfma_f32_16x16x32_bf16 v[212:215], v[184:187], v[24:27], 0
	v_mfma_f32_16x16x32_bf16 v[216:219], v[184:187], v[28:31], 0
	s_nop 0
	ds_write_b128 v252, v[188:191]
	ds_write_b128 v252, v[192:195] offset:1280
	ds_write_b128 v252, v[196:199] offset:2560
	ds_write_b128 v252, v[200:203] offset:3840
	ds_write_b128 v252, v[204:207] offset:5120
	ds_write_b128 v252, v[208:211] offset:6400
	ds_write_b128 v252, v[212:215] offset:7680
	ds_write_b128 v252, v[216:219] offset:8960
	s_waitcnt lgkmcnt(0)
	ds_read_b128 v[220:223], v253
	ds_read_b128 v[236:239], v253 offset:5120
	ds_read_b128 v[224:227], v253 offset:16
	ds_read_b128 v[240:243], v253 offset:5136
	ds_read_b128 v[228:231], v253 offset:32
	ds_read_b128 v[244:247], v253 offset:5152
	ds_read_b128 v[232:235], v253 offset:48
	ds_read_b128 v[248:251], v253 offset:5168
	s_waitcnt lgkmcnt(6)
	v_fma_f32 v184, -v132, v89, v220
	v_fma_f32 v185, v132, v88, v236
	v_fma_f32 v88, v128, v88, v184
	v_fma_f32 v89, v128, v89, v185
	v_fma_f32 v184, -v132, v89, v221
	v_fma_f32 v185, v132, v88, v237
	v_fma_f32 v88, v128, v88, v184
	v_fma_f32 v89, v128, v89, v185
	v_fma_f32 v184, -v132, v89, v222
	v_fma_f32 v185, v132, v88, v238
	v_fma_f32 v88, v128, v88, v184
	v_fma_f32 v89, v128, v89, v185
	v_fma_f32 v184, -v132, v89, v223
	v_fma_f32 v185, v132, v88, v239
	v_fma_f32 v88, v128, v88, v184
	v_fma_f32 v89, v128, v89, v185
	s_waitcnt lgkmcnt(4)
	v_fma_f32 v184, -v132, v89, v224
	v_fma_f32 v185, v132, v88, v240
	v_fma_f32 v88, v128, v88, v184
	v_fma_f32 v89, v128, v89, v185
	v_fma_f32 v184, -v132, v89, v225
	v_fma_f32 v185, v132, v88, v241
	v_fma_f32 v88, v128, v88, v184
	v_fma_f32 v89, v128, v89, v185
	v_fma_f32 v184, -v132, v89, v226
	v_fma_f32 v185, v132, v88, v242
	v_fma_f32 v88, v128, v88, v184
	v_fma_f32 v89, v128, v89, v185
	v_fma_f32 v184, -v132, v89, v227
	v_fma_f32 v185, v132, v88, v243
	v_fma_f32 v88, v128, v88, v184
	v_fma_f32 v89, v128, v89, v185
	s_waitcnt lgkmcnt(2)
	v_fma_f32 v184, -v132, v89, v228
	v_fma_f32 v185, v132, v88, v244
	v_fma_f32 v88, v128, v88, v184
	v_fma_f32 v89, v128, v89, v185
	v_fma_f32 v184, -v132, v89, v229
	v_fma_f32 v185, v132, v88, v245
	v_fma_f32 v88, v128, v88, v184
	v_fma_f32 v89, v128, v89, v185
	v_fma_f32 v184, -v132, v89, v230
	v_fma_f32 v185, v132, v88, v246
	v_fma_f32 v88, v128, v88, v184
	v_fma_f32 v89, v128, v89, v185
	v_fma_f32 v184, -v132, v89, v231
	v_fma_f32 v185, v132, v88, v247
	v_fma_f32 v88, v128, v88, v184
	v_fma_f32 v89, v128, v89, v185
	s_waitcnt lgkmcnt(0)
	v_fma_f32 v184, -v132, v89, v232
	v_fma_f32 v185, v132, v88, v248
	v_fma_f32 v88, v128, v88, v184
	v_fma_f32 v89, v128, v89, v185
	v_fma_f32 v184, -v132, v89, v233
	v_fma_f32 v185, v132, v88, v249
	v_fma_f32 v88, v128, v88, v184
	v_fma_f32 v89, v128, v89, v185
	v_fma_f32 v184, -v132, v89, v234
	v_fma_f32 v185, v132, v88, v250
	v_fma_f32 v88, v128, v88, v184
	v_fma_f32 v89, v128, v89, v185
	v_fma_f32 v184, -v132, v89, v235
	v_fma_f32 v185, v132, v88, v251
	v_fma_f32 v88, v128, v88, v184
	v_fma_f32 v89, v128, v89, v185
	v_cndmask_b32_e64 v184, v76, 0, s[10:11]
	v_cndmask_b32_e64 v185, v77, 0, s[10:11]
	v_cndmask_b32_e64 v186, v78, 0, s[10:11]
	v_cndmask_b32_e64 v187, v79, 0, s[10:11]
	s_nop 1
	v_mfma_f32_16x16x32_bf16 v[188:191], v[184:187], v[0:3], 0
	v_mfma_f32_16x16x32_bf16 v[192:195], v[184:187], v[4:7], 0
	v_mfma_f32_16x16x32_bf16 v[196:199], v[184:187], v[8:11], 0
	v_mfma_f32_16x16x32_bf16 v[200:203], v[184:187], v[12:15], 0
	v_mfma_f32_16x16x32_bf16 v[204:207], v[184:187], v[16:19], 0
	v_mfma_f32_16x16x32_bf16 v[208:211], v[184:187], v[20:23], 0
	v_mfma_f32_16x16x32_bf16 v[212:215], v[184:187], v[24:27], 0
	v_mfma_f32_16x16x32_bf16 v[216:219], v[184:187], v[28:31], 0
	s_nop 0
	ds_write_b128 v252, v[188:191]
	ds_write_b128 v252, v[192:195] offset:1280
	ds_write_b128 v252, v[196:199] offset:2560
	ds_write_b128 v252, v[200:203] offset:3840
	ds_write_b128 v252, v[204:207] offset:5120
	ds_write_b128 v252, v[208:211] offset:6400
	ds_write_b128 v252, v[212:215] offset:7680
	ds_write_b128 v252, v[216:219] offset:8960
	s_waitcnt lgkmcnt(0)
	ds_read_b128 v[220:223], v253
	ds_read_b128 v[236:239], v253 offset:5120
	ds_read_b128 v[224:227], v253 offset:16
	ds_read_b128 v[240:243], v253 offset:5136
	ds_read_b128 v[228:231], v253 offset:32
	ds_read_b128 v[244:247], v253 offset:5152
	ds_read_b128 v[232:235], v253 offset:48
	ds_read_b128 v[248:251], v253 offset:5168
	s_waitcnt lgkmcnt(6)
	v_fma_f32 v184, -v132, v89, v220
	v_fma_f32 v185, v132, v88, v236
	v_fma_f32 v88, v128, v88, v184
	v_fma_f32 v89, v128, v89, v185
	v_fma_f32 v184, -v132, v89, v221
	v_fma_f32 v185, v132, v88, v237
	v_fma_f32 v88, v128, v88, v184
	v_fma_f32 v89, v128, v89, v185
	v_fma_f32 v184, -v132, v89, v222
	v_fma_f32 v185, v132, v88, v238
	v_fma_f32 v88, v128, v88, v184
	v_fma_f32 v89, v128, v89, v185
	v_fma_f32 v184, -v132, v89, v223
	v_fma_f32 v185, v132, v88, v239
	v_fma_f32 v88, v128, v88, v184
	v_fma_f32 v89, v128, v89, v185
	s_waitcnt lgkmcnt(4)
	v_fma_f32 v184, -v132, v89, v224
	v_fma_f32 v185, v132, v88, v240
	v_fma_f32 v88, v128, v88, v184
	v_fma_f32 v89, v128, v89, v185
	v_fma_f32 v184, -v132, v89, v225
	v_fma_f32 v185, v132, v88, v241
	v_fma_f32 v88, v128, v88, v184
	v_fma_f32 v89, v128, v89, v185
	v_fma_f32 v184, -v132, v89, v226
	v_fma_f32 v185, v132, v88, v242
	v_fma_f32 v88, v128, v88, v184
	v_fma_f32 v89, v128, v89, v185
	v_fma_f32 v184, -v132, v89, v227
	v_fma_f32 v185, v132, v88, v243
	v_fma_f32 v88, v128, v88, v184
	v_fma_f32 v89, v128, v89, v185
	s_waitcnt lgkmcnt(2)
	v_fma_f32 v184, -v132, v89, v228
	v_fma_f32 v185, v132, v88, v244
	v_fma_f32 v88, v128, v88, v184
	v_fma_f32 v89, v128, v89, v185
	v_fma_f32 v184, -v132, v89, v229
	v_fma_f32 v185, v132, v88, v245
	v_fma_f32 v88, v128, v88, v184
	v_fma_f32 v89, v128, v89, v185
	v_fma_f32 v184, -v132, v89, v230
	v_fma_f32 v185, v132, v88, v246
	v_fma_f32 v88, v128, v88, v184
	v_fma_f32 v89, v128, v89, v185
	v_fma_f32 v184, -v132, v89, v231
	v_fma_f32 v185, v132, v88, v247
	v_fma_f32 v88, v128, v88, v184
	v_fma_f32 v89, v128, v89, v185
	s_waitcnt lgkmcnt(0)
	v_fma_f32 v184, -v132, v89, v232
	v_fma_f32 v185, v132, v88, v248
	v_fma_f32 v88, v128, v88, v184
	v_fma_f32 v89, v128, v89, v185
	v_fma_f32 v184, -v132, v89, v233
	v_fma_f32 v185, v132, v88, v249
	v_fma_f32 v88, v128, v88, v184
	v_fma_f32 v89, v128, v89, v185
	v_fma_f32 v184, -v132, v89, v234
	v_fma_f32 v185, v132, v88, v250
	v_fma_f32 v88, v128, v88, v184
	v_fma_f32 v89, v128, v89, v185
	v_fma_f32 v184, -v132, v89, v235
	v_fma_f32 v185, v132, v88, v251
	v_fma_f32 v88, v128, v88, v184
	v_fma_f32 v89, v128, v89, v185
	v_cndmask_b32_e64 v184, v72, 0, s[10:11]
	v_cndmask_b32_e64 v185, v73, 0, s[10:11]
	v_cndmask_b32_e64 v186, v74, 0, s[10:11]
	v_cndmask_b32_e64 v187, v75, 0, s[10:11]
	s_nop 1
	v_mfma_f32_16x16x32_bf16 v[188:191], v[184:187], v[0:3], 0
	v_mfma_f32_16x16x32_bf16 v[192:195], v[184:187], v[4:7], 0
	v_mfma_f32_16x16x32_bf16 v[196:199], v[184:187], v[8:11], 0
	v_mfma_f32_16x16x32_bf16 v[200:203], v[184:187], v[12:15], 0
	v_mfma_f32_16x16x32_bf16 v[204:207], v[184:187], v[16:19], 0
	v_mfma_f32_16x16x32_bf16 v[208:211], v[184:187], v[20:23], 0
	v_mfma_f32_16x16x32_bf16 v[212:215], v[184:187], v[24:27], 0
	v_mfma_f32_16x16x32_bf16 v[216:219], v[184:187], v[28:31], 0
	s_nop 0
	ds_write_b128 v252, v[188:191]
	ds_write_b128 v252, v[192:195] offset:1280
	ds_write_b128 v252, v[196:199] offset:2560
	ds_write_b128 v252, v[200:203] offset:3840
	ds_write_b128 v252, v[204:207] offset:5120
	ds_write_b128 v252, v[208:211] offset:6400
	ds_write_b128 v252, v[212:215] offset:7680
	ds_write_b128 v252, v[216:219] offset:8960
	s_waitcnt lgkmcnt(0)
	ds_read_b128 v[220:223], v253
	ds_read_b128 v[236:239], v253 offset:5120
	ds_read_b128 v[224:227], v253 offset:16
	ds_read_b128 v[240:243], v253 offset:5136
	ds_read_b128 v[228:231], v253 offset:32
	ds_read_b128 v[244:247], v253 offset:5152
	ds_read_b128 v[232:235], v253 offset:48
	ds_read_b128 v[248:251], v253 offset:5168
	s_waitcnt lgkmcnt(6)
	v_fma_f32 v184, -v132, v89, v220
	v_fma_f32 v185, v132, v88, v236
	v_fma_f32 v88, v128, v88, v184
	v_fma_f32 v89, v128, v89, v185
	v_fma_f32 v184, -v132, v89, v221
	v_fma_f32 v185, v132, v88, v237
	v_fma_f32 v88, v128, v88, v184
	v_fma_f32 v89, v128, v89, v185
	v_fma_f32 v184, -v132, v89, v222
	v_fma_f32 v185, v132, v88, v238
	v_fma_f32 v88, v128, v88, v184
	v_fma_f32 v89, v128, v89, v185
	v_fma_f32 v184, -v132, v89, v223
	v_fma_f32 v185, v132, v88, v239
	v_fma_f32 v88, v128, v88, v184
	v_fma_f32 v89, v128, v89, v185
	s_waitcnt lgkmcnt(4)
	v_fma_f32 v184, -v132, v89, v224
	v_fma_f32 v185, v132, v88, v240
	v_fma_f32 v88, v128, v88, v184
	v_fma_f32 v89, v128, v89, v185
	v_fma_f32 v184, -v132, v89, v225
	v_fma_f32 v185, v132, v88, v241
	v_fma_f32 v88, v128, v88, v184
	v_fma_f32 v89, v128, v89, v185
	v_fma_f32 v184, -v132, v89, v226
	v_fma_f32 v185, v132, v88, v242
	v_fma_f32 v88, v128, v88, v184
	v_fma_f32 v89, v128, v89, v185
	v_fma_f32 v184, -v132, v89, v227
	v_fma_f32 v185, v132, v88, v243
	v_fma_f32 v88, v128, v88, v184
	v_fma_f32 v89, v128, v89, v185
	s_waitcnt lgkmcnt(2)
	v_fma_f32 v184, -v132, v89, v228
	v_fma_f32 v185, v132, v88, v244
	v_fma_f32 v88, v128, v88, v184
	v_fma_f32 v89, v128, v89, v185
	v_fma_f32 v184, -v132, v89, v229
	v_fma_f32 v185, v132, v88, v245
	v_fma_f32 v88, v128, v88, v184
	v_fma_f32 v89, v128, v89, v185
	v_fma_f32 v184, -v132, v89, v230
	v_fma_f32 v185, v132, v88, v246
	v_fma_f32 v88, v128, v88, v184
	v_fma_f32 v89, v128, v89, v185
	v_fma_f32 v184, -v132, v89, v231
	v_fma_f32 v185, v132, v88, v247
	v_fma_f32 v88, v128, v88, v184
	v_fma_f32 v89, v128, v89, v185
	s_waitcnt lgkmcnt(0)
	v_fma_f32 v184, -v132, v89, v232
	v_fma_f32 v185, v132, v88, v248
	v_fma_f32 v88, v128, v88, v184
	v_fma_f32 v89, v128, v89, v185
	v_fma_f32 v184, -v132, v89, v233
	v_fma_f32 v185, v132, v88, v249
	v_fma_f32 v88, v128, v88, v184
	v_fma_f32 v89, v128, v89, v185
	v_fma_f32 v184, -v132, v89, v234
	v_fma_f32 v185, v132, v88, v250
	v_fma_f32 v88, v128, v88, v184
	v_fma_f32 v89, v128, v89, v185
	v_fma_f32 v184, -v132, v89, v235
	v_fma_f32 v185, v132, v88, v251
	v_fma_f32 v88, v128, v88, v184
	v_fma_f32 v89, v128, v89, v185
	v_cndmask_b32_e64 v184, v68, 0, s[10:11]
	v_cndmask_b32_e64 v185, v69, 0, s[10:11]
	v_cndmask_b32_e64 v186, v70, 0, s[10:11]
	v_cndmask_b32_e64 v187, v71, 0, s[10:11]
	s_nop 1
	v_mfma_f32_16x16x32_bf16 v[188:191], v[184:187], v[0:3], 0
	v_mfma_f32_16x16x32_bf16 v[192:195], v[184:187], v[4:7], 0
	v_mfma_f32_16x16x32_bf16 v[196:199], v[184:187], v[8:11], 0
	v_mfma_f32_16x16x32_bf16 v[200:203], v[184:187], v[12:15], 0
	v_mfma_f32_16x16x32_bf16 v[204:207], v[184:187], v[16:19], 0
	v_mfma_f32_16x16x32_bf16 v[208:211], v[184:187], v[20:23], 0
	v_mfma_f32_16x16x32_bf16 v[212:215], v[184:187], v[24:27], 0
	v_mfma_f32_16x16x32_bf16 v[216:219], v[184:187], v[28:31], 0
	s_nop 0
	ds_write_b128 v252, v[188:191]
	ds_write_b128 v252, v[192:195] offset:1280
	ds_write_b128 v252, v[196:199] offset:2560
	ds_write_b128 v252, v[200:203] offset:3840
	ds_write_b128 v252, v[204:207] offset:5120
	ds_write_b128 v252, v[208:211] offset:6400
	ds_write_b128 v252, v[212:215] offset:7680
	ds_write_b128 v252, v[216:219] offset:8960
	s_waitcnt lgkmcnt(0)
	ds_read_b128 v[220:223], v253
	ds_read_b128 v[236:239], v253 offset:5120
	ds_read_b128 v[224:227], v253 offset:16
	ds_read_b128 v[240:243], v253 offset:5136
	ds_read_b128 v[228:231], v253 offset:32
	ds_read_b128 v[244:247], v253 offset:5152
	ds_read_b128 v[232:235], v253 offset:48
	ds_read_b128 v[248:251], v253 offset:5168
	s_waitcnt lgkmcnt(6)
	v_fma_f32 v184, -v132, v89, v220
	v_fma_f32 v185, v132, v88, v236
	v_fma_f32 v88, v128, v88, v184
	v_fma_f32 v89, v128, v89, v185
	v_fma_f32 v184, -v132, v89, v221
	v_fma_f32 v185, v132, v88, v237
	v_fma_f32 v88, v128, v88, v184
	v_fma_f32 v89, v128, v89, v185
	v_fma_f32 v184, -v132, v89, v222
	v_fma_f32 v185, v132, v88, v238
	v_fma_f32 v88, v128, v88, v184
	v_fma_f32 v89, v128, v89, v185
	v_fma_f32 v184, -v132, v89, v223
	v_fma_f32 v185, v132, v88, v239
	v_fma_f32 v88, v128, v88, v184
	v_fma_f32 v89, v128, v89, v185
	s_waitcnt lgkmcnt(4)
	v_fma_f32 v184, -v132, v89, v224
	v_fma_f32 v185, v132, v88, v240
	v_fma_f32 v88, v128, v88, v184
	v_fma_f32 v89, v128, v89, v185
	v_fma_f32 v184, -v132, v89, v225
	v_fma_f32 v185, v132, v88, v241
	v_fma_f32 v88, v128, v88, v184
	v_fma_f32 v89, v128, v89, v185
	v_fma_f32 v184, -v132, v89, v226
	v_fma_f32 v185, v132, v88, v242
	v_fma_f32 v88, v128, v88, v184
	v_fma_f32 v89, v128, v89, v185
	v_fma_f32 v184, -v132, v89, v227
	v_fma_f32 v185, v132, v88, v243
	v_fma_f32 v88, v128, v88, v184
	v_fma_f32 v89, v128, v89, v185
	s_waitcnt lgkmcnt(2)
	v_fma_f32 v184, -v132, v89, v228
	v_fma_f32 v185, v132, v88, v244
	v_fma_f32 v88, v128, v88, v184
	v_fma_f32 v89, v128, v89, v185
	v_fma_f32 v184, -v132, v89, v229
	v_fma_f32 v185, v132, v88, v245
	v_fma_f32 v88, v128, v88, v184
	v_fma_f32 v89, v128, v89, v185
	v_fma_f32 v184, -v132, v89, v230
	v_fma_f32 v185, v132, v88, v246
	v_fma_f32 v88, v128, v88, v184
	v_fma_f32 v89, v128, v89, v185
	v_fma_f32 v184, -v132, v89, v231
	v_fma_f32 v185, v132, v88, v247
	v_fma_f32 v88, v128, v88, v184
	v_fma_f32 v89, v128, v89, v185
	s_waitcnt lgkmcnt(0)
	v_fma_f32 v184, -v132, v89, v232
	v_fma_f32 v185, v132, v88, v248
	v_fma_f32 v88, v128, v88, v184
	v_fma_f32 v89, v128, v89, v185
	v_fma_f32 v184, -v132, v89, v233
	v_fma_f32 v185, v132, v88, v249
	v_fma_f32 v88, v128, v88, v184
	v_fma_f32 v89, v128, v89, v185
	v_fma_f32 v184, -v132, v89, v234
	v_fma_f32 v185, v132, v88, v250
	v_fma_f32 v88, v128, v88, v184
	v_fma_f32 v89, v128, v89, v185
	v_fma_f32 v184, -v132, v89, v235
	v_fma_f32 v185, v132, v88, v251
	v_fma_f32 v88, v128, v88, v184
	v_fma_f32 v89, v128, v89, v185
	s_add_i32 s34, s34, 1
	s_add_u32 s30, s30, 0x40000
	s_addc_u32 s31, s31, 0
	s_cmp_eq_u32 s30, 0x200000
	s_cbranch_scc1 .LBB0_850
	s_waitcnt vmcnt(0)
	v_mov_b64_e32 v[70:71], v[66:67]
	v_mov_b64_e32 v[74:75], v[62:63]
	v_mov_b64_e32 v[78:79], v[58:59]
	v_mov_b64_e32 v[82:83], v[54:55]
	v_mov_b64_e32 v[68:69], v[64:65]
	v_mov_b64_e32 v[72:73], v[60:61]
	v_mov_b64_e32 v[76:77], v[56:57]
	v_mov_b64_e32 v[80:81], v[52:53]
	s_cmp_gt_u32 s34, 6
	s_cbranch_scc0 .LBB0_847
	s_branch .LBB0_848
